# v24 + GEMM prologue de-serialisation: tile-1 LDS-DMA issued with tile-0, first wait recounted vmcnt(10)
# baseline (speedup 1.0000x reference)
.LBB0_117:
	v_lshrrev_b32_e32 v18, 1, v8
	v_and_b32_e32 v18, 24, v18
	v_readlane_b32 s22, v253, 33
	v_and_b32_e32 v9, 15, v8
	v_lshlrev_b32_e32 v19, 1, v18
	v_lshlrev_b32_e32 v8, 2, v8
	s_lshl_b32 s0, s0, 5
	v_mov_b32_e32 v135, v0
	v_readlane_b32 s23, v253, 34
	v_lshl_or_b32 v1, s1, 6, v9
	v_lshl_or_b32 v9, v9, 6, v19
	s_lshl_b32 s1, s1, 13
	v_and_b32_e32 v8, 32, v8
	s_and_b32 s0, s0, 0x60
	v_lshl_add_u64 v[10:11], s[22:23], 0, v[134:135]
	v_mov_b32_e32 v131, v0
	v_readlane_b32 s20, v253, 29
	v_bitop3_b32 v19, v9, s1, v8 bitop3:0xde
	s_lshl_b32 s1, s0, 7
	v_lshl_add_u64 v[12:13], s[22:23], 0, v[130:131]
	v_mov_b32_e32 v137, v0
	v_readlane_b32 s21, v253, 30
	v_bitop3_b32 v142, v9, s1, v8 bitop3:0xde
	s_add_i32 m0, s27, 0x18000
	v_lshl_add_u64 v[8:9], v[10:11], 0, s[78:79]
	v_lshl_add_u64 v[14:15], s[20:21], 0, v[136:137]
	v_mov_b32_e32 v133, v0
	global_load_lds_dwordx4 v[8:9], off
	v_lshl_add_u64 v[8:9], v[12:13], 0, s[78:79]
	s_add_i32 m0, s27, 0x1a000
	s_add_i32 s42, s27, 0x8000
	v_lshl_add_u64 v[16:17], s[20:21], 0, v[132:133]
	global_load_lds_dwordx4 v[8:9], off
	v_lshl_add_u64 v[8:9], v[14:15], 0, s[78:79]
	s_mov_b32 m0, s42
	s_add_i32 s43, s27, 0xa000
	v_readlane_b32 s18, v253, 35
	global_load_lds_dwordx4 v[8:9], off
	v_lshl_add_u64 v[8:9], v[16:17], 0, s[78:79]
	s_mov_b32 m0, s43
	v_readlane_b32 s19, v253, 36
	global_load_lds_dwordx4 v[8:9], off
	s_add_i32 m0, s27, 0x1c000
	v_lshl_add_u64 v[8:9], s[18:19], 0, v[134:135]
	global_load_lds_dwordx4 v[8:9], off
	v_lshl_add_u64 v[8:9], s[18:19], 0, v[130:131]
	s_add_i32 m0, s27, 0x1e000
	v_or_b32_e32 v143, s0, v18
	global_load_lds_dwordx4 v[8:9], off
	s_waitcnt vmcnt(10)
	s_barrier
	v_lshlrev_b32_e32 v8, 15, v6
	v_and_b32_e32 v8, 0xffff0000, v8
	v_lshl_add_u32 v5, v5, 12, v8
	v_and_b32_e32 v6, 1, v6
	v_lshl_or_b32 v5, v6, 6, v5
	v_lshl_add_u32 v138, v7, 1, v5
	v_lshlrev_b32_e32 v5, 15, v2
	v_and_b32_e32 v5, 0xffff0000, v5
	s_waitcnt vmcnt(6)
	v_lshl_add_u32 v3, v3, 12, v5
	v_and_b32_e32 v2, 1, v2
	v_lshl_or_b32 v2, v2, 6, v3
	v_readlane_b32 s0, v254, 25
	v_mov_b32_e32 v139, v0
	v_lshl_add_u32 v140, v4, 1, v2
	v_mov_b32_e32 v141, v0
	s_mov_b32 s44, 0
	v_add_u32_e32 v144, 0, v19
	v_readlane_b32 s45, v253, 24
	s_mov_b32 s46, s0
	s_barrier
	v_readlane_b32 s1, v254, 26

.LBB0_236:
	v_bfe_u32 v18, v8, 4, 2
	v_readlane_b32 s22, v252, 56
	v_and_b32_e32 v9, 15, v8
	v_lshlrev_b32_e32 v19, 4, v18
	v_lshlrev_b32_e32 v8, 2, v8
	s_lshl_b32 s0, s0, 5
	v_mov_b32_e32 v133, v0
	v_readlane_b32 s23, v252, 57
	v_lshl_or_b32 v1, s1, 6, v9
	v_lshl_or_b32 v9, v9, 6, v19
	s_lshl_b32 s1, s1, 13
	v_and_b32_e32 v8, 32, v8
	s_and_b32 s0, s0, 0x60
	v_lshl_add_u64 v[10:11], s[22:23], 0, v[132:133]
	v_mov_b32_e32 v131, v0
	v_readlane_b32 s80, v252, 52
	v_bitop3_b32 v19, v9, s1, v8 bitop3:0xde
	s_lshl_b32 s1, s0, 7
	v_lshl_add_u64 v[12:13], s[22:23], 0, v[130:131]
	v_readlane_b32 s81, v252, 53
	v_bitop3_b32 v138, v9, s1, v8 bitop3:0xde
	s_add_i32 m0, s27, 0x18000
	v_lshl_add_u64 v[8:9], v[10:11], 0, s[78:79]
	v_lshl_add_u64 v[14:15], s[80:81], 0, v[132:133]
	global_load_lds_dwordx4 v[8:9], off
	v_lshl_add_u64 v[8:9], v[12:13], 0, s[78:79]
	s_add_i32 m0, s27, 0x1a000
	s_add_i32 s42, s27, 0x8000
	v_lshl_add_u64 v[16:17], s[80:81], 0, v[130:131]
	global_load_lds_dwordx4 v[8:9], off
	v_lshl_add_u64 v[8:9], v[14:15], 0, s[78:79]
	s_mov_b32 m0, s42
	s_add_i32 s43, s27, 0xa000
	v_readlane_b32 s18, v252, 58
	global_load_lds_dwordx4 v[8:9], off
	v_lshl_add_u64 v[8:9], v[16:17], 0, s[78:79]
	s_mov_b32 m0, s43
	v_readlane_b32 s19, v252, 59
	global_load_lds_dwordx4 v[8:9], off
	s_add_i32 m0, s27, 0x1c000
	v_lshl_add_u64 v[8:9], s[18:19], 0, v[132:133]
	global_load_lds_dwordx4 v[8:9], off
	v_lshl_add_u64 v[8:9], s[18:19], 0, v[130:131]
	s_add_i32 m0, s27, 0x1e000
	v_lshl_or_b32 v139, v18, 2, s0
	global_load_lds_dwordx4 v[8:9], off
	s_waitcnt vmcnt(10)
	s_barrier
	v_lshlrev_b32_e32 v8, 15, v5
	v_and_b32_e32 v8, 0xffff0000, v8
	v_lshl_add_u32 v6, v6, 12, v8
	v_and_b32_e32 v5, 1, v5
	v_lshl_or_b32 v5, v5, 6, v6
	v_lshl_add_u32 v134, v7, 1, v5
	v_lshlrev_b32_e32 v5, 15, v2
	v_and_b32_e32 v5, 0xffff0000, v5
	s_waitcnt vmcnt(6)
	v_lshl_add_u32 v3, v3, 12, v5
	v_and_b32_e32 v2, 1, v2
	v_lshl_or_b32 v2, v2, 6, v3
	v_readlane_b32 s0, v252, 48
	v_mov_b32_e32 v135, v0
	v_lshl_add_u32 v136, v4, 1, v2
	v_mov_b32_e32 v137, v0
	s_mov_b32 s44, 0
	v_add_u32_e32 v140, 0, v19
	v_readlane_b32 s45, v252, 47
	s_mov_b32 s46, s0
	s_barrier
	v_readlane_b32 s1, v252, 49

.LBB0_349:
	v_lshrrev_b32_e32 v18, 1, v8
	v_and_b32_e32 v18, 24, v18
	v_readlane_b32 s22, v253, 43
	v_and_b32_e32 v9, 15, v8
	v_lshlrev_b32_e32 v19, 1, v18
	v_lshlrev_b32_e32 v8, 2, v8
	s_lshl_b32 s18, s18, 5
	v_mov_b32_e32 v135, v0
	v_readlane_b32 s23, v253, 44
	v_lshl_or_b32 v1, s19, 6, v9
	v_lshl_or_b32 v9, v9, 6, v19
	s_lshl_b32 s19, s19, 13
	v_and_b32_e32 v8, 32, v8
	s_and_b32 s18, s18, 0x60
	v_lshl_add_u64 v[10:11], s[22:23], 0, v[134:135]
	v_mov_b32_e32 v131, v0
	v_readlane_b32 s20, v253, 39
	v_bitop3_b32 v19, v9, s19, v8 bitop3:0xde
	s_lshl_b32 s19, s18, 7
	v_lshl_add_u64 v[12:13], s[22:23], 0, v[130:131]
	v_mov_b32_e32 v137, v0
	v_readlane_b32 s21, v253, 40
	v_bitop3_b32 v142, v9, s19, v8 bitop3:0xde
	s_add_i32 m0, s27, 0x18000
	v_lshl_add_u64 v[8:9], v[10:11], 0, s[78:79]
	v_lshl_add_u64 v[14:15], s[20:21], 0, v[136:137]
	v_mov_b32_e32 v133, v0
	global_load_lds_dwordx4 v[8:9], off
	v_lshl_add_u64 v[8:9], v[12:13], 0, s[78:79]
	s_add_i32 m0, s27, 0x1a000
	s_add_i32 s42, s27, 0x8000
	v_lshl_add_u64 v[16:17], s[20:21], 0, v[132:133]
	global_load_lds_dwordx4 v[8:9], off
	v_lshl_add_u64 v[8:9], v[14:15], 0, s[78:79]
	s_mov_b32 m0, s42
	s_add_i32 s43, s27, 0xa000
	v_readlane_b32 s30, v253, 45
	global_load_lds_dwordx4 v[8:9], off
	v_lshl_add_u64 v[8:9], v[16:17], 0, s[78:79]
	s_mov_b32 m0, s43
	v_readlane_b32 s31, v253, 46
	global_load_lds_dwordx4 v[8:9], off
	s_add_i32 m0, s27, 0x1c000
	v_lshl_add_u64 v[8:9], s[30:31], 0, v[134:135]
	global_load_lds_dwordx4 v[8:9], off
	v_lshl_add_u64 v[8:9], s[30:31], 0, v[130:131]
	s_add_i32 m0, s27, 0x1e000
	v_readlane_b32 s4, v254, 25
	global_load_lds_dwordx4 v[8:9], off
	s_waitcnt vmcnt(10)
	s_barrier
	v_lshlrev_b32_e32 v8, 13, v6
	v_and_b32_e32 v8, 0xffffc000, v8
	v_lshl_add_u32 v5, v5, 10, v8
	v_and_b32_e32 v6, 1, v6
	v_lshl_or_b32 v5, v6, 6, v5
	v_lshl_add_u32 v138, v7, 1, v5
	v_lshlrev_b32_e32 v5, 13, v2
	v_and_b32_e32 v5, 0xffffc000, v5
	s_waitcnt vmcnt(6)
	v_lshl_add_u32 v3, v3, 10, v5
	v_and_b32_e32 v2, 1, v2
	v_lshl_or_b32 v2, v2, 6, v3
	v_or_b32_e32 v143, s18, v18
	v_mov_b32_e32 v139, v0
	v_lshl_add_u32 v140, v4, 1, v2
	v_mov_b32_e32 v141, v0
	s_mov_b32 s44, 0
	v_add_u32_e32 v144, 0, v19
	v_readlane_b32 s45, v253, 24
	s_mov_b32 s46, s4
	s_barrier
	v_readlane_b32 s5, v254, 26

.LBB0_365:
	v_lshrrev_b32_e32 v18, 1, v8
	v_and_b32_e32 v18, 24, v18
	v_readlane_b32 s22, v254, 8
	v_and_b32_e32 v9, 15, v8
	v_lshlrev_b32_e32 v19, 1, v18
	v_lshlrev_b32_e32 v8, 2, v8
	s_lshl_b32 s0, s0, 5
	v_mov_b32_e32 v135, v0
	v_readlane_b32 s23, v254, 9
	v_lshl_or_b32 v1, s1, 6, v9
	v_lshl_or_b32 v9, v9, 6, v19
	s_lshl_b32 s1, s1, 13
	v_and_b32_e32 v8, 32, v8
	s_and_b32 s0, s0, 0x60
	v_lshl_add_u64 v[10:11], s[22:23], 0, v[134:135]
	v_mov_b32_e32 v131, v0
	v_readlane_b32 s20, v254, 4
	v_bitop3_b32 v19, v9, s1, v8 bitop3:0xde
	s_lshl_b32 s1, s0, 7
	v_lshl_add_u64 v[12:13], s[22:23], 0, v[130:131]
	v_mov_b32_e32 v137, v0
	v_readlane_b32 s21, v254, 5
	v_bitop3_b32 v142, v9, s1, v8 bitop3:0xde
	s_add_i32 m0, s27, 0x18000
	v_lshl_add_u64 v[8:9], v[10:11], 0, s[78:79]
	v_lshl_add_u64 v[14:15], s[20:21], 0, v[136:137]
	v_mov_b32_e32 v133, v0
	global_load_lds_dwordx4 v[8:9], off
	v_lshl_add_u64 v[8:9], v[12:13], 0, s[78:79]
	s_add_i32 m0, s27, 0x1a000
	s_add_i32 s42, s27, 0x8000
	v_lshl_add_u64 v[16:17], s[20:21], 0, v[132:133]
	global_load_lds_dwordx4 v[8:9], off
	v_lshl_add_u64 v[8:9], v[14:15], 0, s[78:79]
	s_mov_b32 m0, s42
	s_add_i32 s43, s27, 0xa000
	v_readlane_b32 s18, v254, 10
	global_load_lds_dwordx4 v[8:9], off
	v_lshl_add_u64 v[8:9], v[16:17], 0, s[78:79]
	s_mov_b32 m0, s43
	v_readlane_b32 s19, v254, 11
	global_load_lds_dwordx4 v[8:9], off
	s_add_i32 m0, s27, 0x1c000
	v_lshl_add_u64 v[8:9], s[18:19], 0, v[134:135]
	global_load_lds_dwordx4 v[8:9], off
	v_lshl_add_u64 v[8:9], s[18:19], 0, v[130:131]
	s_add_i32 m0, s27, 0x1e000
	v_or_b32_e32 v143, s0, v18
	global_load_lds_dwordx4 v[8:9], off
	s_waitcnt vmcnt(10)
	s_barrier
	v_lshlrev_b32_e32 v8, 13, v6
	v_and_b32_e32 v8, 0xffffc000, v8
	v_lshl_add_u32 v5, v5, 10, v8
	v_and_b32_e32 v6, 1, v6
	v_lshl_or_b32 v5, v6, 6, v5
	v_lshl_add_u32 v138, v7, 1, v5
	v_lshlrev_b32_e32 v5, 13, v2
	v_and_b32_e32 v5, 0xffffc000, v5
	s_waitcnt vmcnt(6)
	v_lshl_add_u32 v3, v3, 10, v5
	v_and_b32_e32 v2, 1, v2
	v_lshl_or_b32 v2, v2, 6, v3
	v_readlane_b32 s0, v253, 48
	v_mov_b32_e32 v139, v0
	v_lshl_add_u32 v140, v4, 1, v2
	v_mov_b32_e32 v141, v0
	s_mov_b32 s44, 0
	v_add_u32_e32 v144, 0, v19
	v_readlane_b32 s45, v253, 47
	s_mov_b32 s46, s0
	s_barrier
	v_readlane_b32 s1, v253, 49

.LBB0_381:
	v_mov_b32_e32 v143, v0
	v_lshrrev_b32_e32 v18, 1, v7
	v_lshl_add_u64 v[10:11], s[20:21], 0, v[142:143]
	v_mov_b32_e32 v139, v0
	v_readlane_b32 s22, v253, 3
	v_and_b32_e32 v18, 24, v18
	s_lshl_b32 s0, s0, 5
	v_lshl_add_u64 v[12:13], s[20:21], 0, v[138:139]
	v_mov_b32_e32 v145, v0
	v_readlane_b32 s23, v253, 4
	v_and_b32_e32 v9, 15, v7
	v_lshlrev_b32_e32 v19, 1, v18
	v_lshlrev_b32_e32 v7, 2, v7
	s_and_b32 s18, s0, 0x60
	s_add_i32 m0, s90, 0x18000
	v_lshl_add_u64 v[10:11], v[10:11], 0, s[78:79]
	v_lshl_add_u64 v[14:15], s[22:23], 0, v[144:145]
	v_mov_b32_e32 v141, v0
	v_lshl_or_b32 v1, s1, 6, v9
	v_lshl_or_b32 v9, v9, 6, v19
	s_lshl_b32 s1, s1, 13
	v_and_b32_e32 v7, 32, v7
	s_lshl_b32 s0, s18, 7
	global_load_lds_dwordx4 v[10:11], off
	v_lshl_add_u64 v[10:11], v[12:13], 0, s[78:79]
	s_add_i32 m0, s90, 0x1a000
	s_add_i32 s25, s90, 0x8000
	s_add_i32 s26, s90, 0xa000
	v_lshl_add_u64 v[16:17], s[22:23], 0, v[140:141]
	v_bitop3_b32 v154, v9, s0, v7 bitop3:0xde
	global_load_lds_dwordx4 v[10:11], off
	v_lshl_add_u64 v[10:11], v[14:15], 0, s[78:79]
	s_mov_b32 m0, s25
	s_add_u32 s0, s20, 0x20080
	v_bitop3_b32 v19, v9, s1, v7 bitop3:0xde
	global_load_lds_dwordx4 v[10:11], off
	v_lshl_add_u64 v[10:11], v[16:17], 0, s[78:79]
	s_mov_b32 m0, s26
	s_addc_u32 s1, s21, 0
	global_load_lds_dwordx4 v[10:11], off
	s_add_i32 m0, s90, 0x1c000
	v_lshl_add_u64 v[10:11], s[0:1], 0, v[142:143]
	global_load_lds_dwordx4 v[10:11], off
	v_lshl_add_u64 v[10:11], s[0:1], 0, v[138:139]
	s_add_i32 m0, s90, 0x1e000
	v_lshlrev_b32_e32 v7, 13, v6
	global_load_lds_dwordx4 v[10:11], off
	s_waitcnt vmcnt(10)
	s_barrier
	v_and_b32_e32 v7, 0xffffc000, v7
	v_lshl_add_u32 v5, v5, 10, v7
	v_and_b32_e32 v6, 1, v6
	v_lshl_or_b32 v5, v6, 6, v5
	v_lshl_add_u32 v146, v8, 1, v5
	v_lshlrev_b32_e32 v5, 13, v2
	v_and_b32_e32 v5, 0xffffc000, v5
	s_waitcnt vmcnt(6)
	v_lshl_add_u32 v3, v3, 10, v5
	v_and_b32_e32 v2, 1, v2
	v_lshl_or_b32 v2, v2, 6, v3
	v_readlane_b32 s0, v253, 1
	v_or_b32_e32 v155, s18, v18
	v_mov_b32_e32 v147, v0
	v_lshl_add_u32 v148, v4, 1, v2
	v_mov_b32_e32 v149, v0
	s_mov_b32 s27, 0
	v_add_u32_e32 v156, 0, v19
	v_readlane_b32 s28, v252, 62
	s_mov_b32 s29, s0
	s_mov_b64 s[18:19], s[22:23]
	s_barrier
	v_readlane_b32 s1, v253, 2
	s_branch .LBB0_383

.LBB0_521:
	v_mov_b32_e32 v135, v0
	v_lshl_add_u64 v[10:11], s[20:21], 0, v[134:135]
	v_mov_b32_e32 v131, v0
	v_readlane_b32 s42, v253, 16
	s_lshl_b32 s1, s1, 5
	v_lshl_add_u64 v[12:13], s[20:21], 0, v[130:131]
	v_mov_b32_e32 v137, v0
	v_readlane_b32 s43, v253, 17
	s_and_b32 s1, s1, 0x60
	s_add_i32 m0, s29, 0x18000
	v_lshl_add_u64 v[10:11], v[10:11], 0, s[78:79]
	v_lshl_add_u64 v[14:15], s[42:43], 0, v[136:137]
	v_mov_b32_e32 v133, v0
	s_lshl_b32 s22, s0, 13
	s_lshl_b32 s23, s1, 7
	global_load_lds_dwordx4 v[10:11], off
	v_lshl_add_u64 v[10:11], v[12:13], 0, s[78:79]
	s_add_i32 m0, s29, 0x1a000
	s_add_i32 s47, s29, 0x8000
	s_add_i32 s48, s29, 0xa000
	v_lshl_add_u64 v[16:17], s[42:43], 0, v[132:133]
	global_load_lds_dwordx4 v[10:11], off
	v_lshl_add_u64 v[10:11], v[14:15], 0, s[78:79]
	s_mov_b32 m0, s47
	s_add_u32 s18, s20, 0x80080
	global_load_lds_dwordx4 v[10:11], off
	v_lshl_add_u64 v[10:11], v[16:17], 0, s[78:79]
	s_mov_b32 m0, s48
	s_addc_u32 s19, s21, 0
	global_load_lds_dwordx4 v[10:11], off
	s_add_i32 m0, s29, 0x1c000
	v_lshl_add_u64 v[10:11], s[18:19], 0, v[134:135]
	global_load_lds_dwordx4 v[10:11], off
	v_lshl_add_u64 v[10:11], s[18:19], 0, v[130:131]
	s_add_i32 m0, s29, 0x1e000
	v_and_b32_e32 v9, 15, v2
	global_load_lds_dwordx4 v[10:11], off
	s_waitcnt vmcnt(10)
	s_barrier
	v_lshrrev_b32_e32 v10, 1, v2
	v_and_b32_e32 v10, 24, v10
	v_lshlrev_b32_e32 v11, 1, v10
	v_lshlrev_b32_e32 v2, 2, v2
	v_lshl_or_b32 v1, s0, 6, v9
	v_lshl_or_b32 v9, v9, 6, v11
	v_and_b32_e32 v2, 32, v2
	v_bitop3_b32 v11, v9, s22, v2 bitop3:0xde
	v_bitop3_b32 v139, v9, s23, v2 bitop3:0xde
	v_lshlrev_b32_e32 v2, 15, v7
	v_and_b32_e32 v2, 0xffff0000, v2
	v_lshl_add_u32 v2, v6, 12, v2
	v_and_b32_e32 v6, 1, v7
	v_lshl_or_b32 v2, v6, 6, v2
	v_lshl_add_u32 v140, v8, 1, v2
	v_lshlrev_b32_e32 v2, 15, v3
	v_and_b32_e32 v2, 0xffff0000, v2
	s_waitcnt vmcnt(6)
	v_lshl_add_u32 v2, v4, 12, v2
	v_and_b32_e32 v3, 1, v3
	v_or_b32_e32 v138, s1, v10
	v_lshl_or_b32 v2, v3, 6, v2
	v_readlane_b32 s0, v253, 14
	v_mov_b32_e32 v141, v0
	v_lshl_add_u32 v142, v5, 1, v2
	v_mov_b32_e32 v143, v0
	s_mov_b32 s49, 0
	v_add_u32_e32 v154, 0, v11
	v_readlane_b32 s50, v253, 11
	s_mov_b32 s36, s0
	s_mov_b64 s[18:19], s[42:43]
	s_barrier
	v_readlane_b32 s1, v253, 15
	s_waitcnt vmcnt(0)
	s_branch .LBB0_523

.LBB0_641:
	v_mov_b32_e32 v135, v0
	v_lshl_add_u64 v[8:9], s[18:19], 0, v[134:135]
	v_mov_b32_e32 v131, v0
	s_waitcnt vmcnt(0)
	v_and_b32_e32 v146, 15, v164
	v_and_b32_e32 v16, 48, v164
	v_lshlrev_b32_e32 v17, 2, v164
	v_lshl_add_u64 v[10:11], s[18:19], 0, v[130:131]
	v_mov_b32_e32 v137, v0
	s_and_b32 s12, s11, 3
	s_lshl_b32 s45, s0, 6
	s_lshl_b32 s0, s0, 13
	v_lshl_or_b32 v16, v146, 6, v16
	v_and_b32_e32 v17, 32, v17
	s_add_i32 m0, s28, 0x18000
	v_lshl_add_u64 v[8:9], v[8:9], 0, s[78:79]
	v_lshl_add_u64 v[12:13], s[38:39], 0, v[136:137]
	v_mov_b32_e32 v133, v0
	v_bitop3_b32 v18, v16, s0, v17 bitop3:0xde
	s_lshl_b32 s0, s12, 12
	global_load_lds_dwordx4 v[8:9], off
	v_lshl_add_u64 v[8:9], v[10:11], 0, s[78:79]
	s_add_i32 m0, s28, 0x1a000
	s_add_i32 s46, s28, 0x8000
	s_add_i32 s47, s28, 0xa000
	v_lshl_add_u64 v[14:15], s[38:39], 0, v[132:133]
	v_bitop3_b32 v147, v16, s0, v17 bitop3:0xde
	global_load_lds_dwordx4 v[8:9], off
	v_lshl_add_u64 v[8:9], v[12:13], 0, s[78:79]
	s_mov_b32 m0, s46
	s_add_u32 s0, s18, 0x80080
	global_load_lds_dwordx4 v[8:9], off
	v_lshl_add_u64 v[8:9], v[14:15], 0, s[78:79]
	s_mov_b32 m0, s47
	s_addc_u32 s1, s19, 0
	global_load_lds_dwordx4 v[8:9], off
	s_add_i32 m0, s28, 0x1c000
	v_lshl_add_u64 v[8:9], s[0:1], 0, v[134:135]
	global_load_lds_dwordx4 v[8:9], off
	v_lshl_add_u64 v[8:9], s[0:1], 0, v[130:131]
	s_add_i32 m0, s28, 0x1e000
	v_readlane_b32 s0, v253, 24
	global_load_lds_dwordx4 v[8:9], off
	s_waitcnt vmcnt(10)
	s_barrier
	v_lshlrev_b32_e32 v8, 15, v6
	v_and_b32_e32 v8, 0xffff0000, v8
	v_lshl_add_u32 v5, v5, 12, v8
	v_and_b32_e32 v6, 1, v6
	v_lshl_or_b32 v5, v6, 6, v5
	v_lshl_add_u32 v138, v7, 1, v5
	v_lshlrev_b32_e32 v5, 15, v2
	v_and_b32_e32 v5, 0xffff0000, v5
	v_lshl_add_u32 v3, v3, 12, v5
	v_and_b32_e32 v2, 1, v2
	s_waitcnt vmcnt(6)
	v_lshl_or_b32 v2, v2, 6, v3
	v_lshl_add_u32 v140, v4, 1, v2
	v_mov_b32_e32 v2, 0
	s_mov_b32 s84, s0
	v_readlane_b32 s0, v254, 25
	v_or_b32_e32 v1, s45, v146
	v_mov_b32_e32 v139, v0
	v_mov_b32_e32 v141, v0
	s_mov_b32 s48, 0
	v_add_u32_e32 v148, 0, v18
	s_mov_b32 s25, s0
	v_mov_b32_e32 v3, v2
	v_mov_b32_e32 v4, v2
	v_mov_b32_e32 v5, v2
	v_mov_b32_e32 v6, v2
	v_mov_b32_e32 v7, v2
	v_mov_b32_e32 v8, v2
	v_mov_b32_e32 v9, v2
	v_mov_b32_e32 v22, v2
	v_mov_b32_e32 v23, v2
	v_mov_b32_e32 v24, v2
	v_mov_b32_e32 v25, v2
	v_mov_b32_e32 v34, v2
	v_mov_b32_e32 v35, v2
	v_mov_b32_e32 v36, v2
	v_mov_b32_e32 v37, v2
	v_mov_b32_e32 v46, v2
	v_mov_b32_e32 v47, v2
	v_mov_b32_e32 v48, v2
	v_mov_b32_e32 v49, v2
	v_mov_b32_e32 v54, v2
	v_mov_b32_e32 v55, v2
	v_mov_b32_e32 v56, v2
	v_mov_b32_e32 v57, v2
	v_mov_b32_e32 v70, v2
	v_mov_b32_e32 v71, v2
	v_mov_b32_e32 v72, v2
	v_mov_b32_e32 v73, v2
	v_mov_b32_e32 v86, v2
	v_mov_b32_e32 v87, v2
	v_mov_b32_e32 v88, v2
	v_mov_b32_e32 v89, v2
	v_mov_b32_e32 v18, v2
	v_mov_b32_e32 v19, v2
	v_mov_b32_e32 v20, v2
	v_mov_b32_e32 v21, v2
	v_mov_b32_e32 v30, v2
	v_mov_b32_e32 v31, v2
	v_mov_b32_e32 v32, v2
	v_mov_b32_e32 v33, v2
	v_mov_b32_e32 v42, v2
	v_mov_b32_e32 v43, v2
	v_mov_b32_e32 v44, v2
	v_mov_b32_e32 v45, v2
	v_mov_b32_e32 v50, v2
	v_mov_b32_e32 v51, v2
	v_mov_b32_e32 v52, v2
	v_mov_b32_e32 v53, v2
	v_mov_b32_e32 v66, v2
	v_mov_b32_e32 v67, v2
	v_mov_b32_e32 v68, v2
	v_mov_b32_e32 v69, v2
	v_mov_b32_e32 v82, v2
	v_mov_b32_e32 v83, v2
	v_mov_b32_e32 v84, v2
	v_mov_b32_e32 v85, v2
	v_mov_b32_e32 v98, v2
	v_mov_b32_e32 v99, v2
	v_mov_b32_e32 v100, v2
	v_mov_b32_e32 v101, v2
	v_mov_b32_e32 v110, v2
	v_mov_b32_e32 v111, v2
	v_mov_b32_e32 v112, v2
	v_mov_b32_e32 v113, v2
	v_mov_b32_e32 v78, v2
	v_mov_b32_e32 v79, v2
	v_mov_b32_e32 v80, v2
	v_mov_b32_e32 v81, v2
	v_mov_b32_e32 v74, v2
	v_mov_b32_e32 v75, v2
	v_mov_b32_e32 v76, v2
	v_mov_b32_e32 v77, v2
	v_mov_b32_e32 v62, v2
	v_mov_b32_e32 v63, v2
	v_mov_b32_e32 v64, v2
	v_mov_b32_e32 v65, v2
	v_mov_b32_e32 v58, v2
	v_mov_b32_e32 v59, v2
	v_mov_b32_e32 v60, v2
	v_mov_b32_e32 v61, v2
	v_mov_b32_e32 v38, v2
	v_mov_b32_e32 v39, v2
	v_mov_b32_e32 v40, v2
	v_mov_b32_e32 v41, v2
	v_mov_b32_e32 v26, v2
	v_mov_b32_e32 v27, v2
	v_mov_b32_e32 v28, v2
	v_mov_b32_e32 v29, v2
	v_mov_b32_e32 v14, v2
	v_mov_b32_e32 v15, v2
	v_mov_b32_e32 v16, v2
	v_mov_b32_e32 v17, v2
	v_mov_b32_e32 v10, v2
	v_mov_b32_e32 v11, v2
	v_mov_b32_e32 v12, v2
	v_mov_b32_e32 v13, v2
	v_mov_b32_e32 v126, v2
	v_mov_b32_e32 v127, v2
	v_mov_b32_e32 v128, v2
	v_mov_b32_e32 v129, v2
	v_mov_b32_e32 v122, v2
	v_mov_b32_e32 v123, v2
	v_mov_b32_e32 v124, v2
	v_mov_b32_e32 v125, v2
	v_mov_b32_e32 v118, v2
	v_mov_b32_e32 v119, v2
	v_mov_b32_e32 v120, v2
	v_mov_b32_e32 v121, v2
	v_mov_b32_e32 v114, v2
	v_mov_b32_e32 v115, v2
	v_mov_b32_e32 v116, v2
	v_mov_b32_e32 v117, v2
	v_mov_b32_e32 v106, v2
	v_mov_b32_e32 v107, v2
	v_mov_b32_e32 v108, v2
	v_mov_b32_e32 v109, v2
	v_mov_b32_e32 v102, v2
	v_mov_b32_e32 v103, v2
	v_mov_b32_e32 v104, v2
	v_mov_b32_e32 v105, v2
	v_mov_b32_e32 v94, v2
	v_mov_b32_e32 v95, v2
	v_mov_b32_e32 v96, v2
	v_mov_b32_e32 v97, v2
	v_mov_b32_e32 v90, v2
	v_mov_b32_e32 v91, v2
	v_mov_b32_e32 v92, v2
	v_mov_b32_e32 v93, v2
	s_barrier
	v_readlane_b32 s1, v254, 26

.LBB0_741:
	v_readlane_b32 s42, v254, 19
	s_lshl_b32 s1, s1, 5
	v_mov_b32_e32 v137, v0
	v_readlane_b32 s43, v254, 20
	s_and_b32 s1, s1, 0x60
	s_add_i32 m0, s44, 0x18000
	v_lshl_add_u64 v[2:3], v[2:3], 0, s[78:79]
	v_lshl_add_u64 v[12:13], s[42:43], 0, v[136:137]
	v_mov_b32_e32 v133, v0
	s_lshl_b32 s22, s0, 13
	s_lshl_b32 s23, s1, 7
	global_load_lds_dwordx4 v[2:3], off
	v_lshl_add_u64 v[2:3], v[4:5], 0, s[78:79]
	s_add_i32 m0, s44, 0x1a000
	s_add_i32 s48, s44, 0x8000
	s_add_i32 s49, s44, 0xa000
	v_lshl_add_u64 v[14:15], s[42:43], 0, v[132:133]
	global_load_lds_dwordx4 v[2:3], off
	v_lshl_add_u64 v[2:3], v[12:13], 0, s[78:79]
	s_mov_b32 m0, s48
	s_add_u32 s18, s20, 0x80080
	global_load_lds_dwordx4 v[2:3], off
	v_lshl_add_u64 v[2:3], v[14:15], 0, s[78:79]
	s_mov_b32 m0, s49
	s_addc_u32 s19, s21, 0
	global_load_lds_dwordx4 v[2:3], off
	s_add_i32 m0, s44, 0x1c000
	v_lshl_add_u64 v[2:3], s[18:19], 0, v[134:135]
	global_load_lds_dwordx4 v[2:3], off
	v_lshl_add_u64 v[2:3], s[18:19], 0, v[130:131]
	s_add_i32 m0, s44, 0x1e000
	v_mov_b32_e32 v139, v0
	global_load_lds_dwordx4 v[2:3], off
	s_waitcnt vmcnt(10)
	s_barrier
	v_and_b32_e32 v2, 15, v1
	v_lshrrev_b32_e32 v3, 1, v1
	v_lshlrev_b32_e32 v4, 6, v2
	v_lshlrev_b32_e32 v2, 8, v2
	v_and_b32_e32 v3, 24, v3
	v_lshl_or_b32 v2, s0, 14, v2
	v_or3_b32 v138, s1, v2, v3
	v_lshlrev_b32_e32 v2, 15, v10
	v_and_b32_e32 v2, 0xffff0000, v2
	v_lshl_or_b32 v4, v3, 1, v4
	v_lshl_add_u32 v2, v9, 12, v2
	v_and_b32_e32 v3, 1, v10
	v_lshl_or_b32 v2, v3, 6, v2
	v_lshl_add_u32 v154, v11, 1, v2
	v_lshlrev_b32_e32 v2, 15, v6
	v_lshlrev_b32_e32 v1, 2, v1
	v_and_b32_e32 v2, 0xffff0000, v2
	v_and_b32_e32 v1, 32, v1
	s_waitcnt vmcnt(6)
	v_lshl_add_u32 v2, v7, 12, v2
	v_and_b32_e32 v3, 1, v6
	v_bitop3_b32 v5, v4, s22, v1 bitop3:0xde
	v_lshl_or_b32 v2, v3, 6, v2
	v_readlane_b32 s0, v254, 17
	v_bitop3_b32 v1, v4, s23, v1 bitop3:0xde
	v_or_b32_e32 v140, 0x1000, v138
	v_mov_b32_e32 v141, v0
	v_or_b32_e32 v142, 0x2000, v138
	v_mov_b32_e32 v143, v0
	s_waitcnt vmcnt(0)
	v_or_b32_e32 v144, 0x3000, v138
	v_mov_b32_e32 v145, v0
	v_add_u32_e32 v146, 0x8000, v138
	v_mov_b32_e32 v147, v0
	v_add_u32_e32 v148, 0x9000, v138
	v_mov_b32_e32 v149, v0
	v_add_u32_e32 v150, 0xa000, v138
	v_mov_b32_e32 v151, v0
	v_add_u32_e32 v152, 0xb000, v138
	v_mov_b32_e32 v153, v0
	v_mov_b32_e32 v155, v0
	v_lshl_add_u32 v156, v8, 1, v2
	v_mov_b32_e32 v157, v0
	s_mov_b32 s50, 0
	v_add_u32_e32 v158, 0, v5
	v_readlane_b32 s51, v254, 12
	s_mov_b32 s52, s0
	s_mov_b64 s[18:19], s[42:43]
	s_barrier
	v_readlane_b32 s1, v254, 18

.LBB0_805:
	v_mov_b32_e32 v135, v0
	v_lshl_add_u64 v[2:3], s[30:31], 0, v[134:135]
	v_mov_b32_e32 v131, v0
	v_readlane_b32 s84, v254, 29
	v_and_b32_e32 v138, 15, v166
	v_and_b32_e32 v10, 48, v166
	v_lshlrev_b32_e32 v11, 2, v166
	v_lshl_add_u64 v[4:5], s[30:31], 0, v[130:131]
	v_mov_b32_e32 v137, v0
	v_readlane_b32 s85, v254, 30
	s_and_b32 s10, s9, 3
	s_lshl_b32 s46, s0, 6
	s_lshl_b32 s0, s0, 13
	v_lshl_or_b32 v10, v138, 6, v10
	v_and_b32_e32 v11, 32, v11
	s_add_i32 m0, s28, 0x18000
	v_lshl_add_u64 v[2:3], v[2:3], 0, s[78:79]
	v_lshl_add_u64 v[6:7], s[84:85], 0, v[136:137]
	v_mov_b32_e32 v133, v0
	v_bitop3_b32 v12, v10, s0, v11 bitop3:0xde
	s_lshl_b32 s0, s10, 12
	global_load_lds_dwordx4 v[2:3], off
	v_lshl_add_u64 v[2:3], v[4:5], 0, s[78:79]
	s_add_i32 m0, s28, 0x1a000
	s_add_i32 s47, s28, 0x8000
	s_add_i32 s48, s28, 0xa000
	v_lshl_add_u64 v[8:9], s[84:85], 0, v[132:133]
	v_bitop3_b32 v139, v10, s0, v11 bitop3:0xde
	global_load_lds_dwordx4 v[2:3], off
	v_lshl_add_u64 v[2:3], v[6:7], 0, s[78:79]
	s_mov_b32 m0, s47
	s_add_u32 s0, s30, 0x200080
	global_load_lds_dwordx4 v[2:3], off
	v_lshl_add_u64 v[2:3], v[8:9], 0, s[78:79]
	s_mov_b32 m0, s48
	s_addc_u32 s1, s31, 0
	global_load_lds_dwordx4 v[2:3], off
	s_add_i32 m0, s28, 0x1c000
	v_lshl_add_u64 v[2:3], s[0:1], 0, v[134:135]
	global_load_lds_dwordx4 v[2:3], off
	v_lshl_add_u64 v[2:3], s[0:1], 0, v[130:131]
	s_add_i32 m0, s28, 0x1e000
	v_readlane_b32 s0, v253, 24
	global_load_lds_dwordx4 v[2:3], off
	s_waitcnt vmcnt(10)
	s_barrier
	s_waitcnt vmcnt(6)
	v_mov_b32_e32 v58, 0
	s_mov_b32 s80, s0
	v_readlane_b32 s0, v254, 25
	v_or_b32_e32 v1, s46, v138
	s_mov_b32 s49, 0
	v_add_u32_e32 v140, 0, v12
	s_mov_b32 s25, s0
	v_mov_b32_e32 v59, v58
	v_mov_b32_e32 v60, v58
	v_mov_b32_e32 v61, v58
	v_mov_b32_e32 v62, v58
	v_mov_b32_e32 v63, v58
	v_mov_b32_e32 v64, v58
	v_mov_b32_e32 v65, v58
	v_mov_b32_e32 v50, v58
	v_mov_b32_e32 v51, v58
	v_mov_b32_e32 v52, v58
	v_mov_b32_e32 v53, v58
	v_mov_b32_e32 v54, v58
	v_mov_b32_e32 v55, v58
	v_mov_b32_e32 v56, v58
	v_mov_b32_e32 v57, v58
	v_mov_b32_e32 v42, v58
	v_mov_b32_e32 v43, v58
	v_mov_b32_e32 v44, v58
	v_mov_b32_e32 v45, v58
	v_mov_b32_e32 v46, v58
	v_mov_b32_e32 v47, v58
	v_mov_b32_e32 v48, v58
	v_mov_b32_e32 v49, v58
	v_mov_b32_e32 v34, v58
	v_mov_b32_e32 v35, v58
	v_mov_b32_e32 v36, v58
	v_mov_b32_e32 v37, v58
	v_mov_b32_e32 v38, v58
	v_mov_b32_e32 v39, v58
	v_mov_b32_e32 v40, v58
	v_mov_b32_e32 v41, v58
	v_mov_b32_e32 v66, v58
	v_mov_b32_e32 v67, v58
	v_mov_b32_e32 v68, v58
	v_mov_b32_e32 v69, v58
	v_mov_b32_e32 v70, v58
	v_mov_b32_e32 v71, v58
	v_mov_b32_e32 v72, v58
	v_mov_b32_e32 v73, v58
	v_mov_b32_e32 v74, v58
	v_mov_b32_e32 v75, v58
	v_mov_b32_e32 v76, v58
	v_mov_b32_e32 v77, v58
	v_mov_b32_e32 v78, v58
	v_mov_b32_e32 v79, v58
	v_mov_b32_e32 v80, v58
	v_mov_b32_e32 v81, v58
	v_mov_b32_e32 v82, v58
	v_mov_b32_e32 v83, v58
	v_mov_b32_e32 v84, v58
	v_mov_b32_e32 v85, v58
	v_mov_b32_e32 v90, v58
	v_mov_b32_e32 v91, v58
	v_mov_b32_e32 v92, v58
	v_mov_b32_e32 v93, v58
	v_mov_b32_e32 v106, v58
	v_mov_b32_e32 v107, v58
	v_mov_b32_e32 v108, v58
	v_mov_b32_e32 v109, v58
	v_mov_b32_e32 v110, v58
	v_mov_b32_e32 v111, v58
	v_mov_b32_e32 v112, v58
	v_mov_b32_e32 v113, v58
	v_mov_b32_e32 v26, v58
	v_mov_b32_e32 v27, v58
	v_mov_b32_e32 v28, v58
	v_mov_b32_e32 v29, v58
	v_mov_b32_e32 v30, v58
	v_mov_b32_e32 v31, v58
	v_mov_b32_e32 v32, v58
	v_mov_b32_e32 v33, v58
	v_mov_b32_e32 v18, v58
	v_mov_b32_e32 v19, v58
	v_mov_b32_e32 v20, v58
	v_mov_b32_e32 v21, v58
	v_mov_b32_e32 v22, v58
	v_mov_b32_e32 v23, v58
	v_mov_b32_e32 v24, v58
	v_mov_b32_e32 v25, v58
	v_mov_b32_e32 v14, v58
	v_mov_b32_e32 v15, v58
	v_mov_b32_e32 v16, v58
	v_mov_b32_e32 v17, v58
	v_mov_b32_e32 v10, v58
	v_mov_b32_e32 v11, v58
	v_mov_b32_e32 v12, v58
	v_mov_b32_e32 v13, v58
	v_mov_b32_e32 v6, v58
	v_mov_b32_e32 v7, v58
	v_mov_b32_e32 v8, v58
	v_mov_b32_e32 v9, v58
	v_mov_b32_e32 v2, v58
	v_mov_b32_e32 v3, v58
	v_mov_b32_e32 v4, v58
	v_mov_b32_e32 v5, v58
	v_mov_b32_e32 v118, v58
	v_mov_b32_e32 v119, v58
	v_mov_b32_e32 v120, v58
	v_mov_b32_e32 v121, v58
	v_mov_b32_e32 v126, v58
	v_mov_b32_e32 v127, v58
	v_mov_b32_e32 v128, v58
	v_mov_b32_e32 v129, v58
	v_mov_b32_e32 v122, v58
	v_mov_b32_e32 v123, v58
	v_mov_b32_e32 v124, v58
	v_mov_b32_e32 v125, v58
	v_mov_b32_e32 v114, v58
	v_mov_b32_e32 v115, v58
	v_mov_b32_e32 v116, v58
	v_mov_b32_e32 v117, v58
	v_mov_b32_e32 v102, v58
	v_mov_b32_e32 v103, v58
	v_mov_b32_e32 v104, v58
	v_mov_b32_e32 v105, v58
	v_mov_b32_e32 v98, v58
	v_mov_b32_e32 v99, v58
	v_mov_b32_e32 v100, v58
	v_mov_b32_e32 v101, v58
	v_mov_b32_e32 v94, v58
	v_mov_b32_e32 v95, v58
	v_mov_b32_e32 v96, v58
	v_mov_b32_e32 v97, v58
	v_mov_b32_e32 v86, v58
	v_mov_b32_e32 v87, v58
	v_mov_b32_e32 v88, v58
	v_mov_b32_e32 v89, v58
	s_barrier
	v_readlane_b32 s1, v254, 26
	s_branch .LBB0_807
